# code placement: the six large GEMM K-loop heads aligned to 64 bytes
# speedup vs baseline: 1.0044x; 1.0004x over previous
; template <class Epi>
; DI void gemm_phase(LAS unsigned char* lds, const Gemm g, const StaticOrder& S, const Epi& E, int wv0) {
;     ...
;     Acc acc;
; #pragma unroll
;     for (int a = 0; a < 2; ++a)
; #pragma unroll
;         for (int b = 0; b < 2; ++b)
; #pragma unroll
;             for (int m = 0; m < 4; ++m)
; #pragma unroll
;                 for (int n = 0; n < 2; ++n) acc[a][b][m][n] = (f32x4){0.f, 0.f, 0.f, 0.f};
;     ...
;         const bool has_next = S.next(ui + 1, nxt);
;         const char* nA = has_next ? (const char*)g.A + (size_t)nxt.pm * tstepA : cA; const char* nB = has_next ? (const char*)g.Bt + (size_t)nxt.pn * tstepB : cB;
;         for (int t = 0; t < nt; t += 2) {
;             const bool last = (t == nt - 2);
;             const char* a1 = cA + (size_t)(t + 1) * kstep;
;             const char* a2 = last ? nA : cA + (size_t)(t + 2) * kstep; const char* b2 = last ? nB : cB + (size_t)(t + 2) * kstep;
;             const char* a3 = a2 + kstep; const char* b3 = b2 + kstep;
.LBB0_416:
	s_ashr_i32 s11, s10, 31
	s_lshl_b64 s[12:13], s[10:11], 19
	s_add_u32 s12, s24, s12
	s_addc_u32 s13, s25, s13
	s_and_b64 s[14:15], s[2:3], exec
	s_cselect_b32 s11, s13, s19
	s_cselect_b32 s53, s12, s18
	s_ashr_i32 s9, s8, 31
	s_lshl_b64 s[14:15], s[8:9], 19
	s_add_u32 s14, s22, s14
	s_addc_u32 s15, s23, s15
	s_and_b64 s[20:21], s[2:3], exec
	s_cselect_b32 s9, s15, s17
	s_cselect_b32 s54, s14, s16
	s_add_u32 s55, s16, 0x100
	s_addc_u32 s56, s17, 0
	s_add_u32 s16, s18, 0x40080
	v_mov_b32_e32 v2, 0
	s_addc_u32 s17, s19, 0
	s_mov_b32 s57, -2
	v_mov_b32_e32 v3, v2
	v_mov_b32_e32 v4, v2
	v_mov_b32_e32 v5, v2
	v_mov_b32_e32 v6, v2
	v_mov_b32_e32 v7, v2
	v_mov_b32_e32 v8, v2
	v_mov_b32_e32 v9, v2
	v_mov_b32_e32 v18, v2
	v_mov_b32_e32 v19, v2
	v_mov_b32_e32 v20, v2
	v_mov_b32_e32 v21, v2
	v_mov_b32_e32 v22, v2
	v_mov_b32_e32 v23, v2
	v_mov_b32_e32 v24, v2
	v_mov_b32_e32 v25, v2
	v_mov_b32_e32 v34, v2
	v_mov_b32_e32 v35, v2
	v_mov_b32_e32 v36, v2
	v_mov_b32_e32 v37, v2
	v_mov_b32_e32 v38, v2
	v_mov_b32_e32 v39, v2
	v_mov_b32_e32 v40, v2
	v_mov_b32_e32 v41, v2
	v_mov_b32_e32 v50, v2
	v_mov_b32_e32 v51, v2
	v_mov_b32_e32 v52, v2
	v_mov_b32_e32 v53, v2
	v_mov_b32_e32 v54, v2
	v_mov_b32_e32 v55, v2
	v_mov_b32_e32 v56, v2
	v_mov_b32_e32 v57, v2
	v_mov_b32_e32 v10, v2
	v_mov_b32_e32 v11, v2
	v_mov_b32_e32 v12, v2
	v_mov_b32_e32 v13, v2
	v_mov_b32_e32 v14, v2
	v_mov_b32_e32 v15, v2
	v_mov_b32_e32 v16, v2
	v_mov_b32_e32 v17, v2
	v_mov_b32_e32 v26, v2
	v_mov_b32_e32 v27, v2
	v_mov_b32_e32 v28, v2
	v_mov_b32_e32 v29, v2
	v_mov_b32_e32 v30, v2
	v_mov_b32_e32 v31, v2
	v_mov_b32_e32 v32, v2
	v_mov_b32_e32 v33, v2
	v_mov_b32_e32 v42, v2
	v_mov_b32_e32 v43, v2
	v_mov_b32_e32 v44, v2
	v_mov_b32_e32 v45, v2
	v_mov_b32_e32 v46, v2
	v_mov_b32_e32 v47, v2
	v_mov_b32_e32 v48, v2
	v_mov_b32_e32 v49, v2
	v_mov_b32_e32 v58, v2
	v_mov_b32_e32 v59, v2
	v_mov_b32_e32 v60, v2
	v_mov_b32_e32 v61, v2
	v_mov_b32_e32 v62, v2
	v_mov_b32_e32 v63, v2
	v_mov_b32_e32 v64, v2
	v_mov_b32_e32 v65, v2
	v_mov_b32_e32 v66, v2
	v_mov_b32_e32 v67, v2
	v_mov_b32_e32 v68, v2
	v_mov_b32_e32 v69, v2
	v_mov_b32_e32 v70, v2
	v_mov_b32_e32 v71, v2
	v_mov_b32_e32 v72, v2
	v_mov_b32_e32 v73, v2
	v_mov_b32_e32 v82, v2
	v_mov_b32_e32 v83, v2
	v_mov_b32_e32 v84, v2
	v_mov_b32_e32 v85, v2
	v_mov_b32_e32 v86, v2
	v_mov_b32_e32 v87, v2
	v_mov_b32_e32 v88, v2
	v_mov_b32_e32 v89, v2
	v_mov_b32_e32 v98, v2
	v_mov_b32_e32 v99, v2
	v_mov_b32_e32 v100, v2
	v_mov_b32_e32 v101, v2
	v_mov_b32_e32 v102, v2
	v_mov_b32_e32 v103, v2
	v_mov_b32_e32 v104, v2
	v_mov_b32_e32 v105, v2
	v_mov_b32_e32 v114, v2
	v_mov_b32_e32 v115, v2
	v_mov_b32_e32 v116, v2
	v_mov_b32_e32 v117, v2
	v_mov_b32_e32 v118, v2
	v_mov_b32_e32 v119, v2
	v_mov_b32_e32 v120, v2
	v_mov_b32_e32 v121, v2
	v_mov_b32_e32 v74, v2
	v_mov_b32_e32 v75, v2
	v_mov_b32_e32 v76, v2
	v_mov_b32_e32 v77, v2
	v_mov_b32_e32 v78, v2
	v_mov_b32_e32 v79, v2
	v_mov_b32_e32 v80, v2
	v_mov_b32_e32 v81, v2
	v_mov_b32_e32 v90, v2
	v_mov_b32_e32 v91, v2
	v_mov_b32_e32 v92, v2
	v_mov_b32_e32 v93, v2
	v_mov_b32_e32 v94, v2
	v_mov_b32_e32 v95, v2
	v_mov_b32_e32 v96, v2
	v_mov_b32_e32 v97, v2
	v_mov_b32_e32 v106, v2
	v_mov_b32_e32 v107, v2
	v_mov_b32_e32 v108, v2
	v_mov_b32_e32 v109, v2
	v_mov_b32_e32 v110, v2
	v_mov_b32_e32 v111, v2
	v_mov_b32_e32 v112, v2
	v_mov_b32_e32 v113, v2
	v_mov_b32_e32 v122, v2
	v_mov_b32_e32 v123, v2
	v_mov_b32_e32 v124, v2
	v_mov_b32_e32 v125, v2
	v_mov_b32_e32 v126, v2
	v_mov_b32_e32 v127, v2
	v_mov_b32_e32 v128, v2
	v_mov_b32_e32 v129, v2
	.p2align	6

; template <class Epi>
; DI void gemm_phase(LAS unsigned char* lds, const Gemm g, const StaticOrder& S, const Epi& E, int wv0) {
;     ...
;     Acc acc;
; #pragma unroll
;     for (int a = 0; a < 2; ++a)
; #pragma unroll
;         for (int b = 0; b < 2; ++b)
; #pragma unroll
;             for (int m = 0; m < 4; ++m)
; #pragma unroll
;                 for (int n = 0; n < 2; ++n) acc[a][b][m][n] = (f32x4){0.f, 0.f, 0.f, 0.f};
.LBB0_484:
	s_add_u32 s49, s12, 0x100
	v_mov_b32_e32 v2, 0
	s_addc_u32 s50, s13, 0
	s_mov_b32 s51, -2
	v_mov_b32_e32 v3, v2
	v_mov_b32_e32 v4, v2
	v_mov_b32_e32 v5, v2
	v_mov_b32_e32 v6, v2
	v_mov_b32_e32 v7, v2
	v_mov_b32_e32 v8, v2
	v_mov_b32_e32 v9, v2
	v_mov_b32_e32 v18, v2
	v_mov_b32_e32 v19, v2
	v_mov_b32_e32 v20, v2
	v_mov_b32_e32 v21, v2
	v_mov_b32_e32 v22, v2
	v_mov_b32_e32 v23, v2
	v_mov_b32_e32 v24, v2
	v_mov_b32_e32 v25, v2
	v_mov_b32_e32 v34, v2
	v_mov_b32_e32 v35, v2
	v_mov_b32_e32 v36, v2
	v_mov_b32_e32 v37, v2
	v_mov_b32_e32 v38, v2
	v_mov_b32_e32 v39, v2
	v_mov_b32_e32 v40, v2
	v_mov_b32_e32 v41, v2
	v_mov_b32_e32 v50, v2
	v_mov_b32_e32 v51, v2
	v_mov_b32_e32 v52, v2
	v_mov_b32_e32 v53, v2
	v_mov_b32_e32 v54, v2
	v_mov_b32_e32 v55, v2
	v_mov_b32_e32 v56, v2
	v_mov_b32_e32 v57, v2
	v_mov_b32_e32 v10, v2
	v_mov_b32_e32 v11, v2
	v_mov_b32_e32 v12, v2
	v_mov_b32_e32 v13, v2
	v_mov_b32_e32 v14, v2
	v_mov_b32_e32 v15, v2
	v_mov_b32_e32 v16, v2
	v_mov_b32_e32 v17, v2
	v_mov_b32_e32 v26, v2
	v_mov_b32_e32 v27, v2
	v_mov_b32_e32 v28, v2
	v_mov_b32_e32 v29, v2
	v_mov_b32_e32 v30, v2
	v_mov_b32_e32 v31, v2
	v_mov_b32_e32 v32, v2
	v_mov_b32_e32 v33, v2
	v_mov_b32_e32 v42, v2
	v_mov_b32_e32 v43, v2
	v_mov_b32_e32 v44, v2
	v_mov_b32_e32 v45, v2
	v_mov_b32_e32 v46, v2
	v_mov_b32_e32 v47, v2
	v_mov_b32_e32 v48, v2
	v_mov_b32_e32 v49, v2
	v_mov_b32_e32 v58, v2
	v_mov_b32_e32 v59, v2
	v_mov_b32_e32 v60, v2
	v_mov_b32_e32 v61, v2
	v_mov_b32_e32 v62, v2
	v_mov_b32_e32 v63, v2
	v_mov_b32_e32 v64, v2
	v_mov_b32_e32 v65, v2
	v_mov_b32_e32 v66, v2
	v_mov_b32_e32 v67, v2
	v_mov_b32_e32 v68, v2
	v_mov_b32_e32 v69, v2
	v_mov_b32_e32 v70, v2
	v_mov_b32_e32 v71, v2
	v_mov_b32_e32 v72, v2
	v_mov_b32_e32 v73, v2
	v_mov_b32_e32 v82, v2
	v_mov_b32_e32 v83, v2
	v_mov_b32_e32 v84, v2
	v_mov_b32_e32 v85, v2
	v_mov_b32_e32 v86, v2
	v_mov_b32_e32 v87, v2
	v_mov_b32_e32 v88, v2
	v_mov_b32_e32 v89, v2
	v_mov_b32_e32 v98, v2
	v_mov_b32_e32 v99, v2
	v_mov_b32_e32 v100, v2
	v_mov_b32_e32 v101, v2
	v_mov_b32_e32 v102, v2
	v_mov_b32_e32 v103, v2
	v_mov_b32_e32 v104, v2
	v_mov_b32_e32 v105, v2
	v_mov_b32_e32 v114, v2
	v_mov_b32_e32 v115, v2
	v_mov_b32_e32 v116, v2
	v_mov_b32_e32 v117, v2
	v_mov_b32_e32 v118, v2
	v_mov_b32_e32 v119, v2
	v_mov_b32_e32 v120, v2
	v_mov_b32_e32 v121, v2
	v_mov_b32_e32 v74, v2
	v_mov_b32_e32 v75, v2
	v_mov_b32_e32 v76, v2
	v_mov_b32_e32 v77, v2
	v_mov_b32_e32 v78, v2
	v_mov_b32_e32 v79, v2
	v_mov_b32_e32 v80, v2
	v_mov_b32_e32 v81, v2
	v_mov_b32_e32 v90, v2
	v_mov_b32_e32 v91, v2
	v_mov_b32_e32 v92, v2
	v_mov_b32_e32 v93, v2
	v_mov_b32_e32 v94, v2
	v_mov_b32_e32 v95, v2
	v_mov_b32_e32 v96, v2
	v_mov_b32_e32 v97, v2
	v_mov_b32_e32 v106, v2
	v_mov_b32_e32 v107, v2
	v_mov_b32_e32 v108, v2
	v_mov_b32_e32 v109, v2
	v_mov_b32_e32 v110, v2
	v_mov_b32_e32 v111, v2
	v_mov_b32_e32 v112, v2
	v_mov_b32_e32 v113, v2
	v_mov_b32_e32 v122, v2
	v_mov_b32_e32 v123, v2
	v_mov_b32_e32 v124, v2
	v_mov_b32_e32 v125, v2
	v_mov_b32_e32 v126, v2
	v_mov_b32_e32 v127, v2
	v_mov_b32_e32 v128, v2
	v_mov_b32_e32 v129, v2
	.p2align	6

; template <class Epi>
; DI void gemm_phase(LAS unsigned char* lds, const Gemm g, const StaticOrder& S, const Epi& E, int wv0) {
;     ...
;     Acc acc;
; #pragma unroll
;     for (int a = 0; a < 2; ++a)
; #pragma unroll
;         for (int b = 0; b < 2; ++b)
; #pragma unroll
;             for (int m = 0; m < 4; ++m)
; #pragma unroll
;                 for (int n = 0; n < 2; ++n) acc[a][b][m][n] = (f32x4){0.f, 0.f, 0.f, 0.f};
;     ...
;         const bool has_next = S.next(ui + 1, nxt);
;         const char* nA = has_next ? (const char*)g.A + (size_t)nxt.pm * tstepA : cA; const char* nB = has_next ? (const char*)g.Bt + (size_t)nxt.pn * tstepB : cB;
;         for (int t = 0; t < nt; t += 2) {
;             const bool last = (t == nt - 2);
;             const char* a1 = cA + (size_t)(t + 1) * kstep;
;             const char* a2 = last ? nA : cA + (size_t)(t + 2) * kstep; const char* b2 = last ? nB : cB + (size_t)(t + 2) * kstep;
;             const char* a3 = a2 + kstep; const char* b3 = b2 + kstep;
.LBB0_600:
	s_ashr_i32 s15, s14, 31
	s_lshl_b64 s[16:17], s[14:15], 19
	s_add_u32 s16, s28, s16
	s_addc_u32 s17, s29, s17
	s_and_b64 s[18:19], s[2:3], exec
	s_cselect_b32 s5, s17, s23
	s_cselect_b32 s11, s16, s22
	s_ashr_i32 s13, s12, 31
	s_lshl_b64 s[18:19], s[12:13], 19
	s_add_u32 s18, s30, s18
	s_addc_u32 s19, s31, s19
	s_and_b64 s[24:25], s[2:3], exec
	s_cselect_b32 s13, s19, s21
	s_cselect_b32 s15, s18, s20
	s_add_u32 s57, s20, 0x100
	s_addc_u32 s58, s21, 0
	s_add_u32 s20, s22, 0x40080
	v_mov_b32_e32 v2, 0
	s_addc_u32 s21, s23, 0
	s_mov_b32 s59, -2
	v_mov_b32_e32 v3, v2
	v_mov_b32_e32 v4, v2
	v_mov_b32_e32 v5, v2
	v_mov_b32_e32 v6, v2
	v_mov_b32_e32 v7, v2
	v_mov_b32_e32 v8, v2
	v_mov_b32_e32 v9, v2
	v_mov_b32_e32 v10, v2
	v_mov_b32_e32 v11, v2
	v_mov_b32_e32 v12, v2
	v_mov_b32_e32 v13, v2
	v_mov_b32_e32 v18, v2
	v_mov_b32_e32 v19, v2
	v_mov_b32_e32 v20, v2
	v_mov_b32_e32 v21, v2
	v_mov_b32_e32 v26, v2
	v_mov_b32_e32 v27, v2
	v_mov_b32_e32 v28, v2
	v_mov_b32_e32 v29, v2
	v_mov_b32_e32 v34, v2
	v_mov_b32_e32 v35, v2
	v_mov_b32_e32 v36, v2
	v_mov_b32_e32 v37, v2
	v_mov_b32_e32 v42, v2
	v_mov_b32_e32 v43, v2
	v_mov_b32_e32 v44, v2
	v_mov_b32_e32 v45, v2
	v_mov_b32_e32 v50, v2
	v_mov_b32_e32 v51, v2
	v_mov_b32_e32 v52, v2
	v_mov_b32_e32 v53, v2
	v_mov_b32_e32 v14, v2
	v_mov_b32_e32 v15, v2
	v_mov_b32_e32 v16, v2
	v_mov_b32_e32 v17, v2
	v_mov_b32_e32 v22, v2
	v_mov_b32_e32 v23, v2
	v_mov_b32_e32 v24, v2
	v_mov_b32_e32 v25, v2
	v_mov_b32_e32 v30, v2
	v_mov_b32_e32 v31, v2
	v_mov_b32_e32 v32, v2
	v_mov_b32_e32 v33, v2
	v_mov_b32_e32 v38, v2
	v_mov_b32_e32 v39, v2
	v_mov_b32_e32 v40, v2
	v_mov_b32_e32 v41, v2
	v_mov_b32_e32 v46, v2
	v_mov_b32_e32 v47, v2
	v_mov_b32_e32 v48, v2
	v_mov_b32_e32 v49, v2
	v_mov_b32_e32 v54, v2
	v_mov_b32_e32 v55, v2
	v_mov_b32_e32 v56, v2
	v_mov_b32_e32 v57, v2
	v_mov_b32_e32 v58, v2
	v_mov_b32_e32 v59, v2
	v_mov_b32_e32 v60, v2
	v_mov_b32_e32 v61, v2
	v_mov_b32_e32 v62, v2
	v_mov_b32_e32 v63, v2
	v_mov_b32_e32 v64, v2
	v_mov_b32_e32 v65, v2
	v_mov_b32_e32 v66, v2
	v_mov_b32_e32 v67, v2
	v_mov_b32_e32 v68, v2
	v_mov_b32_e32 v69, v2
	v_mov_b32_e32 v70, v2
	v_mov_b32_e32 v71, v2
	v_mov_b32_e32 v72, v2
	v_mov_b32_e32 v73, v2
	v_mov_b32_e32 v74, v2
	v_mov_b32_e32 v75, v2
	v_mov_b32_e32 v76, v2
	v_mov_b32_e32 v77, v2
	v_mov_b32_e32 v82, v2
	v_mov_b32_e32 v83, v2
	v_mov_b32_e32 v84, v2
	v_mov_b32_e32 v85, v2
	v_mov_b32_e32 v90, v2
	v_mov_b32_e32 v91, v2
	v_mov_b32_e32 v92, v2
	v_mov_b32_e32 v93, v2
	v_mov_b32_e32 v98, v2
	v_mov_b32_e32 v99, v2
	v_mov_b32_e32 v100, v2
	v_mov_b32_e32 v101, v2
	v_mov_b32_e32 v106, v2
	v_mov_b32_e32 v107, v2
	v_mov_b32_e32 v108, v2
	v_mov_b32_e32 v109, v2
	v_mov_b32_e32 v114, v2
	v_mov_b32_e32 v115, v2
	v_mov_b32_e32 v116, v2
	v_mov_b32_e32 v117, v2
	v_mov_b32_e32 v78, v2
	v_mov_b32_e32 v79, v2
	v_mov_b32_e32 v80, v2
	v_mov_b32_e32 v81, v2
	v_mov_b32_e32 v86, v2
	v_mov_b32_e32 v87, v2
	v_mov_b32_e32 v88, v2
	v_mov_b32_e32 v89, v2
	v_mov_b32_e32 v94, v2
	v_mov_b32_e32 v95, v2
	v_mov_b32_e32 v96, v2
	v_mov_b32_e32 v97, v2
	v_mov_b32_e32 v102, v2
	v_mov_b32_e32 v103, v2
	v_mov_b32_e32 v104, v2
	v_mov_b32_e32 v105, v2
	v_mov_b32_e32 v110, v2
	v_mov_b32_e32 v111, v2
	v_mov_b32_e32 v112, v2
	v_mov_b32_e32 v113, v2
	v_mov_b32_e32 v118, v2
	v_mov_b32_e32 v119, v2
	v_mov_b32_e32 v120, v2
	v_mov_b32_e32 v121, v2
	v_mov_b32_e32 v122, v2
	v_mov_b32_e32 v123, v2
	v_mov_b32_e32 v124, v2
	v_mov_b32_e32 v125, v2
	v_mov_b32_e32 v126, v2
	v_mov_b32_e32 v127, v2
	v_mov_b32_e32 v128, v2
	v_mov_b32_e32 v129, v2
	.p2align	6

; template <class Epi>
; DI void gemm_phase(LAS unsigned char* lds, const Gemm g, const StaticOrder& S, const Epi& E, int wv0) {
;     ...
;     Acc acc;
; #pragma unroll
;     for (int a = 0; a < 2; ++a)
; #pragma unroll
;         for (int b = 0; b < 2; ++b)
; #pragma unroll
;             for (int m = 0; m < 4; ++m)
; #pragma unroll
;                 for (int n = 0; n < 2; ++n) acc[a][b][m][n] = (f32x4){0.f, 0.f, 0.f, 0.f};
;     ...
;         const bool has_next = S.next(ui + 1, nxt);
;         const char* nA = has_next ? (const char*)g.A + (size_t)nxt.pm * tstepA : cA; const char* nB = has_next ? (const char*)g.Bt + (size_t)nxt.pn * tstepB : cB;
;         for (int t = 0; t < nt; t += 2) {
;             const bool last = (t == nt - 2);
;             const char* a1 = cA + (size_t)(t + 1) * kstep;
;             const char* a2 = last ? nA : cA + (size_t)(t + 2) * kstep; const char* b2 = last ? nB : cB + (size_t)(t + 2) * kstep;
;             const char* a3 = a2 + kstep; const char* b3 = b2 + kstep;
.LBB0_1455:
	s_ashr_i32 s13, s12, 31
	s_lshl_b64 s[14:15], s[12:13], 19
	s_add_u32 s14, s27, s14
	s_addc_u32 s15, s28, s15
	s_and_b64 s[16:17], s[2:3], exec
	s_cselect_b32 s13, s15, s21
	s_cselect_b32 s55, s14, s20
	s_ashr_i32 s11, s10, 31
	s_lshl_b64 s[16:17], s[10:11], 19
	s_add_u32 s16, s29, s16
	s_addc_u32 s17, s30, s17
	s_and_b64 s[22:23], s[2:3], exec
	s_cselect_b32 s11, s17, s19
	s_cselect_b32 s56, s16, s18
	s_add_u32 s57, s18, 0x100
	s_addc_u32 s58, s19, 0
	s_add_u32 s18, s20, 0x40080
	v_mov_b32_e32 v2, 0
	s_addc_u32 s19, s21, 0
	s_mov_b32 s59, -2
	v_mov_b32_e32 v3, v2
	v_mov_b32_e32 v4, v2
	v_mov_b32_e32 v5, v2
	v_mov_b32_e32 v6, v2
	v_mov_b32_e32 v7, v2
	v_mov_b32_e32 v8, v2
	v_mov_b32_e32 v9, v2
	v_mov_b32_e32 v18, v2
	v_mov_b32_e32 v19, v2
	v_mov_b32_e32 v20, v2
	v_mov_b32_e32 v21, v2
	v_mov_b32_e32 v22, v2
	v_mov_b32_e32 v23, v2
	v_mov_b32_e32 v24, v2
	v_mov_b32_e32 v25, v2
	v_mov_b32_e32 v34, v2
	v_mov_b32_e32 v35, v2
	v_mov_b32_e32 v36, v2
	v_mov_b32_e32 v37, v2
	v_mov_b32_e32 v38, v2
	v_mov_b32_e32 v39, v2
	v_mov_b32_e32 v40, v2
	v_mov_b32_e32 v41, v2
	v_mov_b32_e32 v50, v2
	v_mov_b32_e32 v51, v2
	v_mov_b32_e32 v52, v2
	v_mov_b32_e32 v53, v2
	v_mov_b32_e32 v54, v2
	v_mov_b32_e32 v55, v2
	v_mov_b32_e32 v56, v2
	v_mov_b32_e32 v57, v2
	v_mov_b32_e32 v10, v2
	v_mov_b32_e32 v11, v2
	v_mov_b32_e32 v12, v2
	v_mov_b32_e32 v13, v2
	v_mov_b32_e32 v14, v2
	v_mov_b32_e32 v15, v2
	v_mov_b32_e32 v16, v2
	v_mov_b32_e32 v17, v2
	v_mov_b32_e32 v26, v2
	v_mov_b32_e32 v27, v2
	v_mov_b32_e32 v28, v2
	v_mov_b32_e32 v29, v2
	v_mov_b32_e32 v30, v2
	v_mov_b32_e32 v31, v2
	v_mov_b32_e32 v32, v2
	v_mov_b32_e32 v33, v2
	v_mov_b32_e32 v42, v2
	v_mov_b32_e32 v43, v2
	v_mov_b32_e32 v44, v2
	v_mov_b32_e32 v45, v2
	v_mov_b32_e32 v46, v2
	v_mov_b32_e32 v47, v2
	v_mov_b32_e32 v48, v2
	v_mov_b32_e32 v49, v2
	v_mov_b32_e32 v58, v2
	v_mov_b32_e32 v59, v2
	v_mov_b32_e32 v60, v2
	v_mov_b32_e32 v61, v2
	v_mov_b32_e32 v62, v2
	v_mov_b32_e32 v63, v2
	v_mov_b32_e32 v64, v2
	v_mov_b32_e32 v65, v2
	v_mov_b32_e32 v66, v2
	v_mov_b32_e32 v67, v2
	v_mov_b32_e32 v68, v2
	v_mov_b32_e32 v69, v2
	v_mov_b32_e32 v70, v2
	v_mov_b32_e32 v71, v2
	v_mov_b32_e32 v72, v2
	v_mov_b32_e32 v73, v2
	s_waitcnt vmcnt(0)
	v_mov_b32_e32 v82, v2
	v_mov_b32_e32 v83, v2
	v_mov_b32_e32 v84, v2
	v_mov_b32_e32 v85, v2
	v_mov_b32_e32 v86, v2
	v_mov_b32_e32 v87, v2
	v_mov_b32_e32 v88, v2
	v_mov_b32_e32 v89, v2
	v_mov_b32_e32 v98, v2
	v_mov_b32_e32 v99, v2
	v_mov_b32_e32 v100, v2
	v_mov_b32_e32 v101, v2
	v_mov_b32_e32 v102, v2
	v_mov_b32_e32 v103, v2
	v_mov_b32_e32 v104, v2
	v_mov_b32_e32 v105, v2
	v_mov_b32_e32 v114, v2
	v_mov_b32_e32 v115, v2
	v_mov_b32_e32 v116, v2
	v_mov_b32_e32 v117, v2
	v_mov_b32_e32 v118, v2
	v_mov_b32_e32 v119, v2
	v_mov_b32_e32 v120, v2
	v_mov_b32_e32 v121, v2
	v_mov_b32_e32 v74, v2
	v_mov_b32_e32 v75, v2
	v_mov_b32_e32 v76, v2
	v_mov_b32_e32 v77, v2
	v_mov_b32_e32 v78, v2
	v_mov_b32_e32 v79, v2
	v_mov_b32_e32 v80, v2
	v_mov_b32_e32 v81, v2
	v_mov_b32_e32 v90, v2
	v_mov_b32_e32 v91, v2
	v_mov_b32_e32 v92, v2
	v_mov_b32_e32 v93, v2
	v_mov_b32_e32 v94, v2
	v_mov_b32_e32 v95, v2
	v_mov_b32_e32 v96, v2
	v_mov_b32_e32 v97, v2
	v_mov_b32_e32 v106, v2
	v_mov_b32_e32 v107, v2
	v_mov_b32_e32 v108, v2
	v_mov_b32_e32 v109, v2
	v_mov_b32_e32 v110, v2
	v_mov_b32_e32 v111, v2
	v_mov_b32_e32 v112, v2
	v_mov_b32_e32 v113, v2
	v_mov_b32_e32 v122, v2
	v_mov_b32_e32 v123, v2
	v_mov_b32_e32 v124, v2
	v_mov_b32_e32 v125, v2
	v_mov_b32_e32 v126, v2
	v_mov_b32_e32 v127, v2
	v_mov_b32_e32 v128, v2
	v_mov_b32_e32 v129, v2
	.p2align	6

; template <class Epi>
; DI void gemm_phase(LAS unsigned char* lds, const Gemm g, const StaticOrder& S, const Epi& E, int wv0) {
;     ...
;     Acc acc;
; #pragma unroll
;     for (int a = 0; a < 2; ++a)
; #pragma unroll
;         for (int b = 0; b < 2; ++b)
; #pragma unroll
;             for (int m = 0; m < 4; ++m)
; #pragma unroll
;                 for (int n = 0; n < 2; ++n) acc[a][b][m][n] = (f32x4){0.f, 0.f, 0.f, 0.f};
;     ...
;         const bool has_next = S.next(ui + 1, nxt);
;         const char* nA = has_next ? (const char*)g.A + (size_t)nxt.pm * tstepA : cA; const char* nB = has_next ? (const char*)g.Bt + (size_t)nxt.pn * tstepB : cB;
;         for (int t = 0; t < nt; t += 2) {
;             const bool last = (t == nt - 2);
;             const char* a1 = cA + (size_t)(t + 1) * kstep;
;             const char* a2 = last ? nA : cA + (size_t)(t + 2) * kstep; const char* b2 = last ? nB : cB + (size_t)(t + 2) * kstep;
;             const char* a3 = a2 + kstep; const char* b3 = b2 + kstep;
.LBB0_1562:
	s_ashr_i32 s11, s10, 31
	s_lshl_b64 s[12:13], s[10:11], 19
	s_add_u32 s12, s24, s12
	s_addc_u32 s13, s25, s13
	s_and_b64 s[14:15], s[2:3], exec
	s_cselect_b32 s11, s13, s19
	s_cselect_b32 s51, s12, s18
	s_ashr_i32 s9, s8, 31
	s_lshl_b64 s[14:15], s[8:9], 19
	s_add_u32 s14, s22, s14
	s_addc_u32 s15, s23, s15
	s_and_b64 s[20:21], s[2:3], exec
	s_cselect_b32 s9, s15, s17
	s_cselect_b32 s52, s14, s16
	s_add_u32 s53, s16, 0x100
	s_addc_u32 s54, s17, 0
	s_add_u32 s16, s18, 0x40080
	v_mov_b32_e32 v2, 0
	s_addc_u32 s17, s19, 0
	s_mov_b32 s55, -2
	v_mov_b32_e32 v3, v2
	v_mov_b32_e32 v4, v2
	v_mov_b32_e32 v5, v2
	v_mov_b32_e32 v6, v2
	v_mov_b32_e32 v7, v2
	v_mov_b32_e32 v8, v2
	v_mov_b32_e32 v9, v2
	v_mov_b32_e32 v18, v2
	v_mov_b32_e32 v19, v2
	v_mov_b32_e32 v20, v2
	v_mov_b32_e32 v21, v2
	v_mov_b32_e32 v22, v2
	v_mov_b32_e32 v23, v2
	v_mov_b32_e32 v24, v2
	v_mov_b32_e32 v25, v2
	v_mov_b32_e32 v34, v2
	v_mov_b32_e32 v35, v2
	v_mov_b32_e32 v36, v2
	v_mov_b32_e32 v37, v2
	v_mov_b32_e32 v38, v2
	v_mov_b32_e32 v39, v2
	v_mov_b32_e32 v40, v2
	v_mov_b32_e32 v41, v2
	v_mov_b32_e32 v50, v2
	v_mov_b32_e32 v51, v2
	v_mov_b32_e32 v52, v2
	v_mov_b32_e32 v53, v2
	v_mov_b32_e32 v54, v2
	v_mov_b32_e32 v55, v2
	v_mov_b32_e32 v56, v2
	v_mov_b32_e32 v57, v2
	v_mov_b32_e32 v10, v2
	v_mov_b32_e32 v11, v2
	v_mov_b32_e32 v12, v2
	v_mov_b32_e32 v13, v2
	v_mov_b32_e32 v14, v2
	v_mov_b32_e32 v15, v2
	v_mov_b32_e32 v16, v2
	v_mov_b32_e32 v17, v2
	v_mov_b32_e32 v26, v2
	v_mov_b32_e32 v27, v2
	v_mov_b32_e32 v28, v2
	v_mov_b32_e32 v29, v2
	v_mov_b32_e32 v30, v2
	v_mov_b32_e32 v31, v2
	v_mov_b32_e32 v32, v2
	v_mov_b32_e32 v33, v2
	v_mov_b32_e32 v42, v2
	v_mov_b32_e32 v43, v2
	v_mov_b32_e32 v44, v2
	v_mov_b32_e32 v45, v2
	v_mov_b32_e32 v46, v2
	v_mov_b32_e32 v47, v2
	v_mov_b32_e32 v48, v2
	v_mov_b32_e32 v49, v2
	v_mov_b32_e32 v58, v2
	v_mov_b32_e32 v59, v2
	v_mov_b32_e32 v60, v2
	v_mov_b32_e32 v61, v2
	v_mov_b32_e32 v62, v2
	v_mov_b32_e32 v63, v2
	v_mov_b32_e32 v64, v2
	v_mov_b32_e32 v65, v2
	v_mov_b32_e32 v66, v2
	v_mov_b32_e32 v67, v2
	v_mov_b32_e32 v68, v2
	v_mov_b32_e32 v69, v2
	v_mov_b32_e32 v70, v2
	v_mov_b32_e32 v71, v2
	v_mov_b32_e32 v72, v2
	v_mov_b32_e32 v73, v2
	v_mov_b32_e32 v82, v2
	v_mov_b32_e32 v83, v2
	v_mov_b32_e32 v84, v2
	v_mov_b32_e32 v85, v2
	v_mov_b32_e32 v86, v2
	v_mov_b32_e32 v87, v2
	v_mov_b32_e32 v88, v2
	v_mov_b32_e32 v89, v2
	v_mov_b32_e32 v98, v2
	v_mov_b32_e32 v99, v2
	v_mov_b32_e32 v100, v2
	v_mov_b32_e32 v101, v2
	v_mov_b32_e32 v102, v2
	v_mov_b32_e32 v103, v2
	v_mov_b32_e32 v104, v2
	v_mov_b32_e32 v105, v2
	v_mov_b32_e32 v114, v2
	v_mov_b32_e32 v115, v2
	v_mov_b32_e32 v116, v2
	v_mov_b32_e32 v117, v2
	v_mov_b32_e32 v118, v2
	v_mov_b32_e32 v119, v2
	v_mov_b32_e32 v120, v2
	v_mov_b32_e32 v121, v2
	v_mov_b32_e32 v74, v2
	v_mov_b32_e32 v75, v2
	v_mov_b32_e32 v76, v2
	v_mov_b32_e32 v77, v2
	v_mov_b32_e32 v78, v2
	v_mov_b32_e32 v79, v2
	v_mov_b32_e32 v80, v2
	v_mov_b32_e32 v81, v2
	v_mov_b32_e32 v90, v2
	v_mov_b32_e32 v91, v2
	v_mov_b32_e32 v92, v2
	v_mov_b32_e32 v93, v2
	v_mov_b32_e32 v94, v2
	v_mov_b32_e32 v95, v2
	v_mov_b32_e32 v96, v2
	v_mov_b32_e32 v97, v2
	v_mov_b32_e32 v106, v2
	v_mov_b32_e32 v107, v2
	v_mov_b32_e32 v108, v2
	v_mov_b32_e32 v109, v2
	v_mov_b32_e32 v110, v2
	v_mov_b32_e32 v111, v2
	v_mov_b32_e32 v112, v2
	v_mov_b32_e32 v113, v2
	v_mov_b32_e32 v122, v2
	v_mov_b32_e32 v123, v2
	v_mov_b32_e32 v124, v2
	v_mov_b32_e32 v125, v2
	v_mov_b32_e32 v126, v2
	v_mov_b32_e32 v127, v2
	v_mov_b32_e32 v128, v2
	v_mov_b32_e32 v129, v2
	.p2align	6

; template <class Epi>
; DI void gemm_phase(LAS unsigned char* lds, const Gemm g, const StaticOrder& S, const Epi& E, int wv0) {
;     ...
;     Acc acc;
; #pragma unroll
;     for (int a = 0; a < 2; ++a)
; #pragma unroll
;         for (int b = 0; b < 2; ++b)
; #pragma unroll
;             for (int m = 0; m < 4; ++m)
; #pragma unroll
;                 for (int n = 0; n < 2; ++n) acc[a][b][m][n] = (f32x4){0.f, 0.f, 0.f, 0.f};
.LBB0_1630:
	s_add_u32 s47, s12, 0x100
	v_mov_b32_e32 v2, 0
	s_addc_u32 s48, s13, 0
	s_mov_b32 s49, -2
	v_mov_b32_e32 v3, v2
	v_mov_b32_e32 v4, v2
	v_mov_b32_e32 v5, v2
	v_mov_b32_e32 v6, v2
	v_mov_b32_e32 v7, v2
	v_mov_b32_e32 v8, v2
	v_mov_b32_e32 v9, v2
	v_mov_b32_e32 v18, v2
	v_mov_b32_e32 v19, v2
	v_mov_b32_e32 v20, v2
	v_mov_b32_e32 v21, v2
	v_mov_b32_e32 v22, v2
	v_mov_b32_e32 v23, v2
	v_mov_b32_e32 v24, v2
	v_mov_b32_e32 v25, v2
	v_mov_b32_e32 v34, v2
	v_mov_b32_e32 v35, v2
	v_mov_b32_e32 v36, v2
	v_mov_b32_e32 v37, v2
	v_mov_b32_e32 v38, v2
	v_mov_b32_e32 v39, v2
	v_mov_b32_e32 v40, v2
	v_mov_b32_e32 v41, v2
	v_mov_b32_e32 v50, v2
	v_mov_b32_e32 v51, v2
	v_mov_b32_e32 v52, v2
	v_mov_b32_e32 v53, v2
	v_mov_b32_e32 v54, v2
	v_mov_b32_e32 v55, v2
	v_mov_b32_e32 v56, v2
	v_mov_b32_e32 v57, v2
	v_mov_b32_e32 v10, v2
	v_mov_b32_e32 v11, v2
	v_mov_b32_e32 v12, v2
	v_mov_b32_e32 v13, v2
	v_mov_b32_e32 v14, v2
	v_mov_b32_e32 v15, v2
	v_mov_b32_e32 v16, v2
	v_mov_b32_e32 v17, v2
	v_mov_b32_e32 v26, v2
	v_mov_b32_e32 v27, v2
	v_mov_b32_e32 v28, v2
	v_mov_b32_e32 v29, v2
	v_mov_b32_e32 v30, v2
	v_mov_b32_e32 v31, v2
	v_mov_b32_e32 v32, v2
	v_mov_b32_e32 v33, v2
	v_mov_b32_e32 v42, v2
	v_mov_b32_e32 v43, v2
	v_mov_b32_e32 v44, v2
	v_mov_b32_e32 v45, v2
	v_mov_b32_e32 v46, v2
	v_mov_b32_e32 v47, v2
	v_mov_b32_e32 v48, v2
	v_mov_b32_e32 v49, v2
	v_mov_b32_e32 v58, v2
	v_mov_b32_e32 v59, v2
	v_mov_b32_e32 v60, v2
	v_mov_b32_e32 v61, v2
	v_mov_b32_e32 v62, v2
	v_mov_b32_e32 v63, v2
	v_mov_b32_e32 v64, v2
	v_mov_b32_e32 v65, v2
	v_mov_b32_e32 v66, v2
	v_mov_b32_e32 v67, v2
	v_mov_b32_e32 v68, v2
	v_mov_b32_e32 v69, v2
	v_mov_b32_e32 v70, v2
	v_mov_b32_e32 v71, v2
	v_mov_b32_e32 v72, v2
	v_mov_b32_e32 v73, v2
	v_mov_b32_e32 v82, v2
	v_mov_b32_e32 v83, v2
	v_mov_b32_e32 v84, v2
	v_mov_b32_e32 v85, v2
	v_mov_b32_e32 v86, v2
	v_mov_b32_e32 v87, v2
	v_mov_b32_e32 v88, v2
	v_mov_b32_e32 v89, v2
	v_mov_b32_e32 v98, v2
	v_mov_b32_e32 v99, v2
	v_mov_b32_e32 v100, v2
	v_mov_b32_e32 v101, v2
	v_mov_b32_e32 v102, v2
	v_mov_b32_e32 v103, v2
	v_mov_b32_e32 v104, v2
	v_mov_b32_e32 v105, v2
	v_mov_b32_e32 v114, v2
	v_mov_b32_e32 v115, v2
	v_mov_b32_e32 v116, v2
	v_mov_b32_e32 v117, v2
	v_mov_b32_e32 v118, v2
	v_mov_b32_e32 v119, v2
	v_mov_b32_e32 v120, v2
	v_mov_b32_e32 v121, v2
	v_mov_b32_e32 v74, v2
	v_mov_b32_e32 v75, v2
	v_mov_b32_e32 v76, v2
	v_mov_b32_e32 v77, v2
	v_mov_b32_e32 v78, v2
	v_mov_b32_e32 v79, v2
	v_mov_b32_e32 v80, v2
	v_mov_b32_e32 v81, v2
	v_mov_b32_e32 v90, v2
	v_mov_b32_e32 v91, v2
	v_mov_b32_e32 v92, v2
	v_mov_b32_e32 v93, v2
	v_mov_b32_e32 v94, v2
	v_mov_b32_e32 v95, v2
	v_mov_b32_e32 v96, v2
	v_mov_b32_e32 v97, v2
	v_mov_b32_e32 v106, v2
	v_mov_b32_e32 v107, v2
	v_mov_b32_e32 v108, v2
	v_mov_b32_e32 v109, v2
	v_mov_b32_e32 v110, v2
	v_mov_b32_e32 v111, v2
	v_mov_b32_e32 v112, v2
	v_mov_b32_e32 v113, v2
	v_mov_b32_e32 v122, v2
	v_mov_b32_e32 v123, v2
	v_mov_b32_e32 v124, v2
	v_mov_b32_e32 v125, v2
	v_mov_b32_e32 v126, v2
	v_mov_b32_e32 v127, v2
	v_mov_b32_e32 v128, v2
	v_mov_b32_e32 v129, v2
	.p2align	6
